# attention pass 2: previous-accumulator and gate loads widened to dwordx4 (permlane16_swap + v_swap)
# baseline (speedup 1.0000x reference)
; __device__ __forceinline__ unsigned cvt_pk_bf16(float lo, float hi) { unsigned r; asm volatile("v_cvt_pk_bf16_f32 %0, %1, %2" : "=v"(r) : "v"(lo), "v"(hi)); return r; }
;     ...
;         mx = fmaxf(mx, __shfl_xor(mx, 16)); mx = fmaxf(mx, __shfl_xor(mx, 32));
;         float l = 0.f;
; #pragma unroll
;         for (int t = 0; t < 10; ++t)
; #pragma unroll
;             for (int i = 0; i < 4; ++i) { const float p = __builtin_amdgcn_exp2f(s[t][i] - mx); s[t][i] = p; l += p; }
;         l += __shfl_xor(l, 16); l += __shfl_xor(l, 32);
;         bf16x8 pf[5];
; #pragma unroll
;         for (int b = 0; b < 5; ++b) { u32x4 u; u.x = pg8::cvt_pk_bf16(s[2 * b][0], s[2 * b][1]); u.y = pg8::cvt_pk_bf16(s[2 * b][2], s[2 * b][3]);
;             u.z = pg8::cvt_pk_bf16(s[2 * b + 1][0], s[2 * b + 1][1]); u.w = pg8::cvt_pk_bf16(s[2 * b + 1][2], s[2 * b + 1][3]); pf[b] = __builtin_bit_cast(bf16x8, u); }
;         float Lp = 0.f; u32x2 pv[8]; u32x2 gv[8];
;         if (PASS > 0) { Lp = LACC[(size_t)qrow * 16 + h];
; #pragma unroll
;             for (int db = 0; db < 8; ++db) pv[db] = *(const u32x2*)((const char*)OACC + ((unsigned)(h * MT + qrow) * 256u + (unsigned)(32 * db + 8 * fq))); }
;         if (PASS == 2) {
; #pragma unroll
;             for (int db = 0; db < 8; ++db) gv[db] = *(const u32x2*)((const char*)RB + ((unsigned)qrow * (unsigned)(LDB * 2) + (unsigned)(h * 256 + 32 * db + 8 * fq))); }
.LBB0_532:
	v_and_b32_e32 v81, 64, v205
	v_xor_b32_e32 v80, 16, v205
	v_add_u32_e32 v81, 64, v81
	v_cmp_lt_i32_e32 vcc, v80, v81
	s_waitcnt lgkmcnt(2)
	v_max_f32_e32 v82, v160, v160
	v_readlane_b32 s35, v255, 20
	v_cndmask_b32_e32 v80, v205, v80, vcc
	v_lshlrev_b32_e32 v88, 2, v80
	ds_bpermute_b32 v80, v88, v160
	s_and_b32 s34, s35, 0xfffff800
	s_and_b64 s[0:1], s[18:19], exec
	s_cselect_b32 s0, s34, 0x2000
	s_add_i32 s2, s2, s0
	s_waitcnt lgkmcnt(0)
	v_max_f32_e32 v80, v80, v80
	v_max_f32_e32 v80, v82, v80
	v_xor_b32_e32 v82, 32, v205
	v_cmp_lt_i32_e32 vcc, v82, v81
	s_mul_i32 s0, s31, 0x6000
	v_readlane_b32 s18, v255, 44
	v_cndmask_b32_e32 v81, v205, v82, vcc
	v_lshlrev_b32_e32 v89, 2, v81
	ds_bpermute_b32 v81, v89, v80
	v_add_u32_e32 v82, s33, v187
	v_lshl_add_u32 v84, v82, 4, s2
	v_ashrrev_i32_e32 v85, 31, v84
	v_lshlrev_b64 v[86:87], 6, v[84:85]
	s_waitcnt lgkmcnt(0)
	v_max_f32_e32 v81, v81, v81
	v_max_f32_e32 v166, v80, v81
	v_sub_f32_e32 v80, v120, v166
	v_exp_f32_e32 v90, v80
	v_sub_f32_e32 v80, v121, v166
	v_exp_f32_e32 v91, v80
	v_sub_f32_e32 v80, v122, v166
	v_exp_f32_e32 v92, v80
	v_sub_f32_e32 v80, v123, v166
	v_exp_f32_e32 v93, v80
	v_sub_f32_e32 v80, v124, v166
	v_exp_f32_e32 v94, v80
	v_sub_f32_e32 v80, v125, v166
	v_exp_f32_e32 v95, v80
	v_sub_f32_e32 v80, v126, v166
	v_exp_f32_e32 v96, v80
	v_sub_f32_e32 v80, v127, v166
	v_exp_f32_e32 v97, v80
	v_sub_f32_e32 v80, v128, v166
	v_exp_f32_e32 v98, v80
	v_sub_f32_e32 v80, v129, v166
	v_exp_f32_e32 v99, v80
	v_sub_f32_e32 v80, v130, v166
	v_exp_f32_e32 v116, v80
	v_sub_f32_e32 v80, v131, v166
	v_exp_f32_e32 v117, v80
	v_sub_f32_e32 v80, v132, v166
	v_exp_f32_e32 v118, v80
	v_sub_f32_e32 v80, v133, v166
	v_exp_f32_e32 v119, v80
	v_sub_f32_e32 v80, v134, v166
	v_exp_f32_e32 v120, v80
	v_sub_f32_e32 v80, v135, v166
	v_exp_f32_e32 v121, v80
	v_sub_f32_e32 v80, v136, v166
	v_exp_f32_e32 v122, v80
	v_sub_f32_e32 v80, v137, v166
	v_exp_f32_e32 v123, v80
	v_sub_f32_e32 v80, v138, v166
	v_exp_f32_e32 v124, v80
	v_sub_f32_e32 v80, v139, v166
	v_exp_f32_e32 v125, v80
	v_sub_f32_e32 v80, v140, v166
	v_exp_f32_e32 v126, v80
	v_sub_f32_e32 v80, v141, v166
	v_exp_f32_e32 v127, v80
	v_sub_f32_e32 v80, v142, v166
	v_exp_f32_e32 v206, v80
	v_sub_f32_e32 v80, v143, v166
	v_exp_f32_e32 v207, v80
	v_sub_f32_e32 v80, v144, v166
	v_exp_f32_e32 v208, v80
	v_sub_f32_e32 v80, v145, v166
	v_exp_f32_e32 v209, v80
	v_sub_f32_e32 v80, v146, v166
	v_exp_f32_e32 v210, v80
	v_sub_f32_e32 v80, v147, v166
	v_exp_f32_e32 v211, v80
	v_sub_f32_e32 v80, v148, v166
	v_exp_f32_e32 v212, v80
	v_sub_f32_e32 v80, v149, v166
	v_exp_f32_e32 v213, v80
	v_sub_f32_e32 v80, v150, v166
	v_exp_f32_e32 v214, v80
	v_sub_f32_e32 v80, v151, v166
	v_exp_f32_e32 v215, v80
	v_sub_f32_e32 v80, v152, v166
	v_exp_f32_e32 v216, v80
	v_sub_f32_e32 v80, v153, v166
	v_exp_f32_e32 v217, v80
	v_sub_f32_e32 v80, v156, v166
	v_exp_f32_e32 v218, v80
	v_sub_f32_e32 v80, v157, v166
	v_exp_f32_e32 v219, v80
	v_sub_f32_e32 v80, v154, v166
	v_exp_f32_e32 v220, v80
	v_sub_f32_e32 v80, v155, v166
	v_exp_f32_e32 v221, v80
	v_sub_f32_e32 v80, v158, v166
	v_lshl_add_u64 v[86:87], s[80:81], 0, v[86:87]
	s_lshl_b32 s2, s31, 2
	v_add_u32_e32 v85, s0, v84
	v_exp_f32_e32 v222, v80
	v_sub_f32_e32 v80, v159, v166
	v_lshl_add_u64 v[86:87], v[86:87], 0, s[2:3]
	v_lshl_or_b32 v85, v85, 8, v201
	v_exp_f32_e32 v223, v80
	v_cvt_pk_bf16_f32 v80, v90, v91
	v_cvt_pk_bf16_f32 v81, v92, v93
	v_cvt_pk_bf16_f32 v82, v94, v95
	v_cvt_pk_bf16_f32 v83, v96, v97
	v_cvt_pk_bf16_f32 v100, v98, v99
	v_cvt_pk_bf16_f32 v101, v116, v117
	v_cvt_pk_bf16_f32 v102, v118, v119
	v_cvt_pk_bf16_f32 v103, v120, v121
	v_cvt_pk_bf16_f32 v104, v122, v123
	v_cvt_pk_bf16_f32 v105, v124, v125
	v_cvt_pk_bf16_f32 v106, v126, v127
	v_cvt_pk_bf16_f32 v107, v206, v207
	v_cvt_pk_bf16_f32 v108, v208, v209
	v_cvt_pk_bf16_f32 v109, v210, v211
	v_cvt_pk_bf16_f32 v110, v212, v213
	v_cvt_pk_bf16_f32 v111, v214, v215
	v_cvt_pk_bf16_f32 v112, v216, v217
	v_cvt_pk_bf16_f32 v113, v218, v219
	v_cvt_pk_bf16_f32 v114, v220, v221
	v_cvt_pk_bf16_f32 v115, v222, v223
	global_load_dword v242, v[86:87], off
	v_and_b32_e32 v245, 16, v168
	v_lshrrev_b32_e32 v246, 1, v245
	v_add_u32_e32 v245, v245, v246
	v_add_u32_e32 v246, v85, v245
	global_load_dwordx4 v[156:159], v246, s[92:93]
	global_load_dwordx4 v[148:151], v246, s[92:93] offset:64
	global_load_dwordx4 v[140:143], v246, s[92:93] offset:128
	global_load_dwordx4 v[132:135], v246, s[92:93] offset:192
	v_lshlrev_b32_e32 v84, 13, v84
	s_lshl_b32 s0, s31, 8
	v_or3_b32 v182, v84, s0, v201
	v_readlane_b32 s19, v255, 45
	v_or_b32_e32 v163, 0x80, v182
	v_or_b32_e32 v167, 32, v182
	v_or_b32_e32 v165, 64, v182
	v_or_b32_e32 v164, 0x60, v182
	s_nop 0
	v_add_u32_e32 v247, v182, v245
	global_load_dwordx4 v[152:155], v247, s[18:19]
	global_load_dwordx4 v[144:147], v247, s[18:19] offset:64
	global_load_dwordx4 v[136:139], v247, s[18:19] offset:128
	global_load_dwordx4 v[128:131], v247, s[18:19] offset:192
	v_or_b32_e32 v162, 0xa0, v182
	v_or_b32_e32 v161, 0xc0, v182
	v_or_b32_e32 v160, 0xe0, v182
	v_add_f32_e32 v84, 0, v90
	v_add_f32_e32 v84, v91, v84
	v_add_f32_e32 v84, v92, v84
	v_add_f32_e32 v84, v93, v84
	v_add_f32_e32 v84, v94, v84
	v_add_f32_e32 v84, v95, v84
	v_add_f32_e32 v84, v96, v84
	v_add_f32_e32 v84, v97, v84
	v_add_f32_e32 v84, v98, v84
	v_add_f32_e32 v84, v99, v84
	v_add_f32_e32 v84, v116, v84
	v_add_f32_e32 v84, v117, v84
	v_add_f32_e32 v84, v118, v84
	v_add_f32_e32 v84, v119, v84
	v_add_f32_e32 v84, v120, v84
	v_add_f32_e32 v84, v121, v84
	v_add_f32_e32 v84, v122, v84
	v_add_f32_e32 v84, v123, v84
	v_add_f32_e32 v84, v124, v84
	v_add_f32_e32 v84, v125, v84
	v_add_f32_e32 v84, v126, v84
	v_add_f32_e32 v84, v127, v84
	v_add_f32_e32 v84, v206, v84
	v_add_f32_e32 v84, v207, v84
	v_add_f32_e32 v84, v208, v84
	v_add_f32_e32 v84, v209, v84
	v_add_f32_e32 v84, v210, v84
	v_add_f32_e32 v84, v211, v84
	v_add_f32_e32 v84, v212, v84
	v_add_f32_e32 v84, v213, v84
	v_add_f32_e32 v84, v214, v84
	v_add_f32_e32 v84, v215, v84
	v_add_f32_e32 v84, v216, v84
	v_add_f32_e32 v84, v217, v84
	v_add_f32_e32 v84, v218, v84
	v_add_f32_e32 v84, v219, v84
	v_add_f32_e32 v84, v220, v84
	v_add_f32_e32 v84, v221, v84
	v_add_f32_e32 v84, v222, v84
	v_add_f32_e32 v84, v223, v84
	ds_bpermute_b32 v85, v88, v84
	s_waitcnt lgkmcnt(0)
; #define LAS __attribute__((address_space(3)))
; #define ATT_LDV(BUF, DB) _Pragma("unroll") for (int b = 0; b < 5; ++b) { vl[BUF][b] = vtr(vbase + (32 * b) * VPITCH + (DB) * 32); vh[BUF][b] = vtr(vbase + (32 * b + 16) * VPITCH + (DB) * 32); }
;     ...
;         f32x4 o[8];
;         const int q4 = (lane & 15) >> 2, p4 = lane & 3;
;         LAS const unsigned char* vbase = lds + VOFF + (16 * ts + 4 * fq + q4) * VPITCH + p4 * 8;
;         {
;             s16x4 vl[2][5], vh[2][5];
;     ...
;             ATT_LDV(0, 0)
; #pragma unroll
;             for (int db = 0; db < 8; ++db) {
;                 if (db + 1 < 8) { ATT_LDV((db + 1) & 1, db + 1) }
;                 __builtin_amdgcn_sched_barrier(0);
;                 o[db] = (f32x4){0.f, 0.f, 0.f, 0.f};
; #pragma unroll
;                 for (int b = 0; b < 5; ++b) { const s16x4 lo = vl[db & 1][b], hi = vh[db & 1][b];
;                     const bf16x8 vf = (bf16x8){lo[0], lo[1], lo[2], lo[3], hi[0], hi[1], hi[2], hi[3]};
;                     o[db] = __builtin_amdgcn_mfma_f32_16x16x32_bf16(vf, pf[b], o[db], 0, 0, 0); }
;                 __builtin_amdgcn_sched_barrier(0);
;             }
	v_add_f32_e32 v243, v84, v85
	ds_bpermute_b32 v244, v89, v243
	ds_read_b64_tr_b16 v[86:87], v202 offset:4608
	ds_read_b64_tr_b16 v[84:85], v202
	ds_read_b64_tr_b16 v[90:91], v202 offset:4640
	ds_read_b64_tr_b16 v[88:89], v202 offset:32
	ds_read_b64_tr_b16 v[92:93], v202 offset:9216
	ds_read_b64_tr_b16 v[94:95], v202 offset:13824
	ds_read_b64_tr_b16 v[98:99], v202 offset:13856
	ds_read_b64_tr_b16 v[96:97], v202 offset:9248
	ds_read_b64_tr_b16 v[116:117], v202 offset:18432
	ds_read_b64_tr_b16 v[118:119], v202 offset:23040
	ds_read_b64_tr_b16 v[122:123], v202 offset:23072
	ds_read_b64_tr_b16 v[120:121], v202 offset:18464
	ds_read_b64_tr_b16 v[124:125], v202 offset:27648
	ds_read_b64_tr_b16 v[126:127], v202 offset:32256
	ds_read_b64_tr_b16 v[208:209], v202 offset:32288
	ds_read_b64_tr_b16 v[206:207], v202 offset:27680
	ds_read_b64_tr_b16 v[210:211], v202 offset:36864
	ds_read_b64_tr_b16 v[212:213], v202 offset:41472
	ds_read_b64_tr_b16 v[216:217], v202 offset:41504
	ds_read_b64_tr_b16 v[214:215], v202 offset:36896
	s_waitcnt lgkmcnt(14)
	v_mfma_f32_16x16x32_bf16 v[84:87], v[84:87], v[80:83], 0
	v_mfma_f32_16x16x32_bf16 v[84:87], v[92:95], v[100:103], v[84:87]
	s_waitcnt lgkmcnt(10)
	v_mfma_f32_16x16x32_bf16 v[84:87], v[116:119], v[104:107], v[84:87]
	s_waitcnt lgkmcnt(6)
	v_mfma_f32_16x16x32_bf16 v[84:87], v[124:127], v[108:111], v[84:87]
	s_waitcnt lgkmcnt(2)
	v_mfma_f32_16x16x32_bf16 v[124:127], v[210:213], v[112:115], v[84:87]
	s_nop 5
	ds_read_b64_tr_b16 v[84:85], v202 offset:9280
	ds_read_b64_tr_b16 v[86:87], v202 offset:13888
	ds_read_b64_tr_b16 v[92:93], v202 offset:18496
	ds_read_b64_tr_b16 v[94:95], v202 offset:23104
	ds_read_b64_tr_b16 v[116:117], v202 offset:27712
	ds_read_b64_tr_b16 v[118:119], v202 offset:32320
	ds_read_b64_tr_b16 v[210:211], v202 offset:64
	ds_read_b64_tr_b16 v[212:213], v202 offset:4672
	ds_read_b64_tr_b16 v[218:219], v202 offset:36928
	ds_read_b64_tr_b16 v[220:221], v202 offset:41536
	v_mfma_f32_16x16x32_bf16 v[88:91], v[88:91], v[80:83], 0
	v_mfma_f32_16x16x32_bf16 v[88:91], v[96:99], v[100:103], v[88:91]
	v_mfma_f32_16x16x32_bf16 v[88:91], v[120:123], v[104:107], v[88:91]
	v_mfma_f32_16x16x32_bf16 v[88:91], v[206:209], v[108:111], v[88:91]
	s_waitcnt lgkmcnt(10)
	v_mfma_f32_16x16x32_bf16 v[120:123], v[214:217], v[112:115], v[88:91]
	s_nop 5
	ds_read_b64_tr_b16 v[88:89], v202 offset:9312
	ds_read_b64_tr_b16 v[90:91], v202 offset:13920
	ds_read_b64_tr_b16 v[96:97], v202 offset:18528
	ds_read_b64_tr_b16 v[98:99], v202 offset:23136
	ds_read_b64_tr_b16 v[206:207], v202 offset:27744
	ds_read_b64_tr_b16 v[208:209], v202 offset:32352
	ds_read_b64_tr_b16 v[214:215], v202 offset:96
	ds_read_b64_tr_b16 v[216:217], v202 offset:4704
	ds_read_b64_tr_b16 v[222:223], v202 offset:36960
	ds_read_b64_tr_b16 v[224:225], v202 offset:41568
	s_waitcnt lgkmcnt(12)
	v_mfma_f32_16x16x32_bf16 v[210:213], v[210:213], v[80:83], 0
	v_mfma_f32_16x16x32_bf16 v[84:87], v[84:87], v[100:103], v[210:213]
	v_mfma_f32_16x16x32_bf16 v[84:87], v[92:95], v[104:107], v[84:87]
	v_mfma_f32_16x16x32_bf16 v[84:87], v[116:119], v[108:111], v[84:87]
	s_waitcnt lgkmcnt(10)
	v_mfma_f32_16x16x32_bf16 v[116:119], v[218:221], v[112:115], v[84:87]
	s_nop 5
	ds_read_b64_tr_b16 v[84:85], v202 offset:9344
	ds_read_b64_tr_b16 v[86:87], v202 offset:13952
	ds_read_b64_tr_b16 v[92:93], v202 offset:18560
	ds_read_b64_tr_b16 v[94:95], v202 offset:23168
	ds_read_b64_tr_b16 v[210:211], v202 offset:27776
	ds_read_b64_tr_b16 v[212:213], v202 offset:32384
	ds_read_b64_tr_b16 v[218:219], v202 offset:128
	ds_read_b64_tr_b16 v[220:221], v202 offset:4736
	ds_read_b64_tr_b16 v[226:227], v202 offset:36992
	ds_read_b64_tr_b16 v[228:229], v202 offset:41600
	s_waitcnt lgkmcnt(12)
	v_mfma_f32_16x16x32_bf16 v[214:217], v[214:217], v[80:83], 0
	v_mfma_f32_16x16x32_bf16 v[88:91], v[88:91], v[100:103], v[214:217]
	v_mfma_f32_16x16x32_bf16 v[88:91], v[96:99], v[104:107], v[88:91]
	v_mfma_f32_16x16x32_bf16 v[88:91], v[206:209], v[108:111], v[88:91]
	s_waitcnt lgkmcnt(10)
	v_mfma_f32_16x16x32_bf16 v[96:99], v[222:225], v[112:115], v[88:91]
	s_nop 5
	ds_read_b64_tr_b16 v[88:89], v202 offset:9376
	ds_read_b64_tr_b16 v[90:91], v202 offset:13984
	ds_read_b64_tr_b16 v[206:207], v202 offset:18592
	ds_read_b64_tr_b16 v[208:209], v202 offset:23200
	ds_read_b64_tr_b16 v[214:215], v202 offset:27808
	ds_read_b64_tr_b16 v[216:217], v202 offset:32416
	ds_read_b64_tr_b16 v[222:223], v202 offset:160
	ds_read_b64_tr_b16 v[224:225], v202 offset:4768
	ds_read_b64_tr_b16 v[230:231], v202 offset:37024
	ds_read_b64_tr_b16 v[232:233], v202 offset:41632
	s_waitcnt lgkmcnt(12)
	v_mfma_f32_16x16x32_bf16 v[218:221], v[218:221], v[80:83], 0
	v_mfma_f32_16x16x32_bf16 v[84:87], v[84:87], v[100:103], v[218:221]
	v_mfma_f32_16x16x32_bf16 v[84:87], v[92:95], v[104:107], v[84:87]
	v_mfma_f32_16x16x32_bf16 v[84:87], v[210:213], v[108:111], v[84:87]
	s_waitcnt lgkmcnt(10)
	v_mfma_f32_16x16x32_bf16 v[92:95], v[226:229], v[112:115], v[84:87]
	s_nop 5
	ds_read_b64_tr_b16 v[84:85], v202 offset:9408
	ds_read_b64_tr_b16 v[86:87], v202 offset:14016
	ds_read_b64_tr_b16 v[210:211], v202 offset:18624
	ds_read_b64_tr_b16 v[212:213], v202 offset:23232
	ds_read_b64_tr_b16 v[218:219], v202 offset:27840
	ds_read_b64_tr_b16 v[220:221], v202 offset:32448
	ds_read_b64_tr_b16 v[226:227], v202 offset:192
	ds_read_b64_tr_b16 v[228:229], v202 offset:4800
	ds_read_b64_tr_b16 v[234:235], v202 offset:37056
	ds_read_b64_tr_b16 v[236:237], v202 offset:41664
	s_waitcnt lgkmcnt(12)
	v_mfma_f32_16x16x32_bf16 v[222:225], v[222:225], v[80:83], 0
	v_mfma_f32_16x16x32_bf16 v[88:91], v[88:91], v[100:103], v[222:225]
	v_mfma_f32_16x16x32_bf16 v[88:91], v[206:209], v[104:107], v[88:91]
	v_mfma_f32_16x16x32_bf16 v[88:91], v[214:217], v[108:111], v[88:91]
	s_waitcnt lgkmcnt(10)
; __device__ __forceinline__ unsigned cvt_pk_bf16(float lo, float hi) { unsigned r; asm volatile("v_cvt_pk_bf16_f32 %0, %1, %2" : "=v"(r) : "v"(lo), "v"(hi)); return r; }
; __device__ __forceinline__ float silu_f(float x) { return x * __builtin_amdgcn_rcpf(1.0f + __builtin_amdgcn_exp2f(-x * LOG2E)); }
;     ...
;                     o[db] = __builtin_amdgcn_mfma_f32_16x16x32_bf16(vf, pf[b], o[db], 0, 0, 0); }
;                 __builtin_amdgcn_sched_barrier(0);
;             }
;     ...
;         }
;         const float rl = 1.0f / l;
;         float Lc = mx + __builtin_amdgcn_logf(l);
;         float wb = rl, wa = 0.f;
;         if (PASS > 0) { const float Lm = fmaxf(Lp, Lc);
;             const float ea = __builtin_amdgcn_exp2f(Lp - Lm), eb = __builtin_amdgcn_exp2f(Lc - Lm), den = ea + eb, rd = 1.0f / den;
;             wa = ea * rd; wb = eb * rd * rl; Lc = Lm + __builtin_amdgcn_logf(den); }
;         if (PASS < 2) { if (fq == 0) LACC[(size_t)qrow * 16 + h] = Lc; }
; #pragma unroll
;         for (int db = 0; db < 8; ++db) { f32x4 v = o[db] * wb;
;             const size_t ocol = (size_t)h * 128 + 16 * db + 4 * fq;
;             if (PASS > 0) { v[0] += wa * bf_lo(pv[db].x); v[1] += wa * bf_hi(pv[db].x); v[2] += wa * bf_lo(pv[db].y); v[3] += wa * bf_hi(pv[db].y); }
;             if (PASS < 2) { u32x2 ov; ov.x = pg8::cvt_pk_bf16(v[0], v[1]); ov.y = pg8::cvt_pk_bf16(v[2], v[3]); *(u32x2*)((char*)OACC + ((unsigned)(h * MT + qrow) * 256u + (unsigned)(32 * db + 8 * fq))) = ov; }
;             else { v[0] *= pg8::silu_f(bf_lo(gv[db].x)); v[1] *= pg8::silu_f(bf_hi(gv[db].x)); v[2] *= pg8::silu_f(bf_lo(gv[db].y)); v[3] *= pg8::silu_f(bf_hi(gv[db].y));
;                 u32x2 ov; ov.x = pg8::cvt_pk_bf16(v[0], v[1]); ov.y = pg8::cvt_pk_bf16(v[2], v[3]); *(u32x2*)((char*)RB + ((unsigned)qrow * (unsigned)(LDB * 2) + (unsigned)(h * 256 + 32 * db + 8 * fq))) = ov; } }
	v_mfma_f32_16x16x32_bf16 v[88:91], v[230:233], v[112:115], v[88:91]
	ds_read_b64_tr_b16 v[206:207], v202 offset:9440
	ds_read_b64_tr_b16 v[208:209], v202 offset:14048
	ds_read_b64_tr_b16 v[214:215], v202 offset:18656
	ds_read_b64_tr_b16 v[216:217], v202 offset:23264
	ds_read_b64_tr_b16 v[222:223], v202 offset:27872
	ds_read_b64_tr_b16 v[224:225], v202 offset:32480
	ds_read_b64_tr_b16 v[230:231], v202 offset:224
	ds_read_b64_tr_b16 v[232:233], v202 offset:4832
	ds_read_b64_tr_b16 v[238:239], v202 offset:37088
	ds_read_b64_tr_b16 v[240:241], v202 offset:41696
	s_waitcnt lgkmcnt(12)
	v_mfma_f32_16x16x32_bf16 v[226:229], v[226:229], v[80:83], 0
	v_mfma_f32_16x16x32_bf16 v[84:87], v[84:87], v[100:103], v[226:229]
	v_mfma_f32_16x16x32_bf16 v[84:87], v[210:213], v[104:107], v[84:87]
	v_mfma_f32_16x16x32_bf16 v[84:87], v[218:221], v[108:111], v[84:87]
	s_waitcnt lgkmcnt(10)
	v_mfma_f32_16x16x32_bf16 v[84:87], v[234:237], v[112:115], v[84:87]
	s_waitcnt lgkmcnt(2)
	v_mfma_f32_16x16x32_bf16 v[80:83], v[230:233], v[80:83], 0
	v_mfma_f32_16x16x32_bf16 v[80:83], v[206:209], v[100:103], v[80:83]
	v_mfma_f32_16x16x32_bf16 v[80:83], v[214:217], v[104:107], v[80:83]
	v_mfma_f32_16x16x32_bf16 v[80:83], v[222:225], v[108:111], v[80:83]
	s_waitcnt lgkmcnt(0)
	v_mfma_f32_16x16x32_bf16 v[80:83], v[238:241], v[112:115], v[80:83]
	v_add_f32_e32 v100, v243, v244
	v_log_f32_e32 v103, v100
	v_div_scale_f32 v101, s[0:1], v100, v100, 1.0
	v_rcp_f32_e32 v102, v101
	v_add_f32_e32 v103, v166, v103
	s_waitcnt vmcnt(8)
	v_max_f32_e32 v106, v242, v242
	v_max_f32_e32 v106, v106, v103
	v_fma_f32 v104, -v101, v102, 1.0
	v_sub_f32_e32 v107, v242, v106
	v_sub_f32_e32 v103, v103, v106
	v_fmac_f32_e32 v102, v104, v102
	v_div_scale_f32 v104, vcc, 1.0, v100, 1.0
	v_exp_f32_e32 v107, v107
	v_exp_f32_e32 v103, v103
	v_mul_f32_e32 v105, v104, v102
	v_fma_f32 v106, -v101, v105, v104
	v_fmac_f32_e32 v105, v106, v102
	v_fma_f32 v101, -v101, v105, v104
	v_add_f32_e32 v104, v107, v103
	v_div_scale_f32 v106, s[0:1], v104, v104, 1.0
	v_rcp_f32_e32 v108, v106
	v_div_fmas_f32 v101, v101, v102, v105
	v_div_fixup_f32 v100, v101, v100, 1.0
	s_waitcnt vmcnt(3)
	v_permlane16_swap_b32_e32 v156, v158
	v_permlane16_swap_b32_e32 v157, v159
	v_permlane16_swap_b32_e32 v152, v154
	v_permlane16_swap_b32_e32 v153, v155
	v_swap_b32 v158, v152
	v_swap_b32 v159, v153
	v_and_b32_e32 v110, 0xffff0000, v158
	v_fma_f32 v101, -v106, v108, 1.0
	v_fmac_f32_e32 v108, v101, v108
	v_div_scale_f32 v101, vcc, 1.0, v104, 1.0
	v_mul_f32_e32 v102, v101, v108
	v_fma_f32 v105, -v106, v102, v101
	v_fmac_f32_e32 v102, v105, v108
	v_fma_f32 v101, -v106, v102, v101
	v_div_fmas_f32 v101, v101, v108, v102
	v_div_fixup_f32 v102, v101, v104, 1.0
	v_mul_f32_e32 v101, v107, v102
	v_mul_f32_e32 v102, v103, v102
	v_lshlrev_b32_e32 v104, 16, v158
	v_mul_f32_e32 v102, v100, v102
	v_mul_f32_e32 v100, 0xbfb8aa3b, v104
	v_exp_f32_e32 v100, v100
	v_pk_mul_f32 v[106:107], v[102:103], v[126:127] op_sel_hi:[0,1]
	v_pk_mul_f32 v[108:109], v[102:103], v[124:125] op_sel_hi:[0,1]
	v_mul_f32_e32 v103, 0xbfb8aa3b, v110
	v_add_f32_e32 v100, 1.0, v100
	v_rcp_f32_e32 v100, v100
	v_lshlrev_b32_e32 v105, 16, v156
	v_exp_f32_e32 v103, v103
	v_and_b32_e32 v111, 0xffff0000, v156
	v_pk_mul_f32 v[104:105], v[100:101], v[104:105]
	v_readlane_b32 s0, v255, 21
	v_add_f32_e32 v100, v105, v108
	v_mul_f32_e32 v112, v104, v100
	v_lshlrev_b32_e32 v104, 16, v159
	v_add_f32_e32 v100, 1.0, v103
	v_mul_f32_e32 v103, 0xbfb8aa3b, v104
	v_rcp_f32_e32 v100, v100
	v_exp_f32_e32 v103, v103
	v_and_b32_e32 v108, 0xffff0000, v159
	s_add_i32 s35, s35, s0
	v_pk_mul_f32 v[110:111], v[100:101], v[110:111]
	v_add_f32_e32 v100, 1.0, v103
	v_mul_f32_e32 v103, 0xbfb8aa3b, v108
	v_rcp_f32_e32 v100, v100
	v_exp_f32_e32 v103, v103
	v_add_f32_e32 v105, v111, v109
	v_mul_f32_e32 v110, v110, v105
	v_lshlrev_b32_e32 v105, 16, v157
	v_pk_mul_f32 v[104:105], v[100:101], v[104:105]
	v_add_f32_e32 v100, 1.0, v103
	v_rcp_f32_e32 v100, v100
	v_add_f32_e32 v103, v105, v106
	v_and_b32_e32 v109, 0xffff0000, v157
	v_mul_f32_e32 v103, v104, v103
	v_pk_mul_f32 v[104:105], v[100:101], v[108:109]
	v_pk_mul_f32 v[108:109], v[102:103], v[120:121] op_sel_hi:[0,1]
	v_add_f32_e32 v100, v105, v107
	v_mul_f32_e32 v100, v104, v100
	v_cvt_pk_bf16_f32 v104, v112, v110
	v_cvt_pk_bf16_f32 v105, v103, v100
	v_mov_b32_e32 v208, v104
	v_mov_b32_e32 v209, v105
	v_and_b32_e32 v224, 16, v168
	v_lshrrev_b32_e32 v225, 1, v224
	v_add_u32_e32 v224, v224, v225
	s_waitcnt vmcnt(3)
	v_lshlrev_b32_e32 v104, 16, v154
	v_mul_f32_e32 v100, 0xbfb8aa3b, v104
	v_exp_f32_e32 v100, v100
	v_and_b32_e32 v110, 0xffff0000, v154
	v_pk_mul_f32 v[106:107], v[102:103], v[122:123] op_sel_hi:[0,1]
	v_mul_f32_e32 v103, 0xbfb8aa3b, v110
	v_add_f32_e32 v100, 1.0, v100
	v_rcp_f32_e32 v100, v100
	v_lshlrev_b32_e32 v105, 16, v152
	v_exp_f32_e32 v103, v103
	v_and_b32_e32 v111, 0xffff0000, v152
	v_pk_mul_f32 v[104:105], v[100:101], v[104:105]
	v_mov_b64_e32 v[126:127], v[66:67]
	v_add_f32_e32 v100, v105, v108
	v_mul_f32_e32 v112, v104, v100
	v_lshlrev_b32_e32 v104, 16, v155
	v_add_f32_e32 v100, 1.0, v103
	v_mul_f32_e32 v103, 0xbfb8aa3b, v104
	v_rcp_f32_e32 v100, v100
	v_exp_f32_e32 v103, v103
	v_and_b32_e32 v108, 0xffff0000, v155
	v_mov_b64_e32 v[122:123], v[78:79]
	v_pk_mul_f32 v[110:111], v[100:101], v[110:111]
	v_add_f32_e32 v100, 1.0, v103
	v_mul_f32_e32 v103, 0xbfb8aa3b, v108
	v_rcp_f32_e32 v100, v100
	v_exp_f32_e32 v103, v103
	v_add_f32_e32 v105, v111, v109
	v_mul_f32_e32 v110, v110, v105
	v_lshlrev_b32_e32 v105, 16, v153
	v_pk_mul_f32 v[104:105], v[100:101], v[104:105]
	v_add_f32_e32 v100, 1.0, v103
	v_rcp_f32_e32 v100, v100
	v_add_f32_e32 v103, v105, v106
	v_and_b32_e32 v109, 0xffff0000, v153
	v_mul_f32_e32 v103, v104, v103
	v_pk_mul_f32 v[104:105], v[100:101], v[108:109]
	v_pk_mul_f32 v[108:109], v[102:103], v[116:117] op_sel_hi:[0,1]
	v_add_f32_e32 v100, v105, v107
	v_mul_f32_e32 v100, v104, v100
	v_cvt_pk_bf16_f32 v104, v112, v110
	v_cvt_pk_bf16_f32 v105, v103, v100
	v_mov_b32_e32 v210, v104
	v_mov_b32_e32 v211, v105
	v_add_u32_e32 v225, v224, v182
	s_nop 0
	v_permlane16_swap_b32_e32 v208, v210
	v_permlane16_swap_b32_e32 v209, v211
	global_store_dwordx4 v225, v[208:211], s[18:19]
	s_waitcnt vmcnt(3)
; __device__ __forceinline__ unsigned cvt_pk_bf16(float lo, float hi) { unsigned r; asm volatile("v_cvt_pk_bf16_f32 %0, %1, %2" : "=v"(r) : "v"(lo), "v"(hi)); return r; }
; __device__ __forceinline__ float silu_f(float x) { return x * __builtin_amdgcn_rcpf(1.0f + __builtin_amdgcn_exp2f(-x * LOG2E)); }
;     ...
;         for (int db = 0; db < 8; ++db) { f32x4 v = o[db] * wb;
;             const size_t ocol = (size_t)h * 128 + 16 * db + 4 * fq;
;             if (PASS > 0) { v[0] += wa * bf_lo(pv[db].x); v[1] += wa * bf_hi(pv[db].x); v[2] += wa * bf_lo(pv[db].y); v[3] += wa * bf_hi(pv[db].y); }
;             if (PASS < 2) { u32x2 ov; ov.x = pg8::cvt_pk_bf16(v[0], v[1]); ov.y = pg8::cvt_pk_bf16(v[2], v[3]); *(u32x2*)((char*)OACC + ((unsigned)(h * MT + qrow) * 256u + (unsigned)(32 * db + 8 * fq))) = ov; }
;             else { v[0] *= pg8::silu_f(bf_lo(gv[db].x)); v[1] *= pg8::silu_f(bf_hi(gv[db].x)); v[2] *= pg8::silu_f(bf_lo(gv[db].y)); v[3] *= pg8::silu_f(bf_hi(gv[db].y));
;                 u32x2 ov; ov.x = pg8::cvt_pk_bf16(v[0], v[1]); ov.y = pg8::cvt_pk_bf16(v[2], v[3]); *(u32x2*)((char*)RB + ((unsigned)qrow * (unsigned)(LDB * 2) + (unsigned)(h * 256 + 32 * db + 8 * fq))) = ov; } }
	v_permlane16_swap_b32_e32 v148, v150
	v_permlane16_swap_b32_e32 v149, v151
	v_permlane16_swap_b32_e32 v144, v146
	v_permlane16_swap_b32_e32 v145, v147
	v_swap_b32 v150, v144
	v_swap_b32 v151, v145
	v_lshlrev_b32_e32 v104, 16, v150
	v_mul_f32_e32 v100, 0xbfb8aa3b, v104
	v_exp_f32_e32 v100, v100
	v_and_b32_e32 v110, 0xffff0000, v150
	v_pk_mul_f32 v[106:107], v[102:103], v[118:119] op_sel_hi:[0,1]
	v_mul_f32_e32 v103, 0xbfb8aa3b, v110
	v_add_f32_e32 v100, 1.0, v100
	v_rcp_f32_e32 v100, v100
	v_lshlrev_b32_e32 v105, 16, v148
	v_exp_f32_e32 v103, v103
	v_and_b32_e32 v111, 0xffff0000, v148
	v_pk_mul_f32 v[104:105], v[100:101], v[104:105]
	v_readlane_b32 s1, v255, 22
	v_add_f32_e32 v100, v105, v108
	v_mul_f32_e32 v112, v104, v100
	v_lshlrev_b32_e32 v104, 16, v151
	v_add_f32_e32 v100, 1.0, v103
	v_mul_f32_e32 v103, 0xbfb8aa3b, v104
	v_rcp_f32_e32 v100, v100
	v_exp_f32_e32 v103, v103
	v_and_b32_e32 v108, 0xffff0000, v151
	v_writelane_b32 v255, s35, 20
	v_pk_mul_f32 v[110:111], v[100:101], v[110:111]
	v_add_f32_e32 v100, 1.0, v103
	v_mul_f32_e32 v103, 0xbfb8aa3b, v108
	v_rcp_f32_e32 v100, v100
	v_exp_f32_e32 v103, v103
	v_add_f32_e32 v105, v111, v109
	v_mul_f32_e32 v110, v110, v105
	v_lshlrev_b32_e32 v105, 16, v149
	v_pk_mul_f32 v[104:105], v[100:101], v[104:105]
	v_add_f32_e32 v100, 1.0, v103
	v_rcp_f32_e32 v100, v100
	v_add_f32_e32 v103, v105, v106
	v_and_b32_e32 v109, 0xffff0000, v149
	v_mul_f32_e32 v103, v104, v103
	v_pk_mul_f32 v[104:105], v[100:101], v[108:109]
	s_waitcnt vmcnt(3)
	v_and_b32_e32 v106, 0xffff0000, v146
	v_add_f32_e32 v100, v105, v107
	v_mul_f32_e32 v100, v104, v100
	v_cvt_pk_bf16_f32 v104, v112, v110
	v_cvt_pk_bf16_f32 v105, v103, v100
	v_mov_b32_e32 v212, v104
	v_mov_b32_e32 v213, v105
	v_lshlrev_b32_e32 v104, 16, v146
	v_mul_f32_e32 v100, 0xbfb8aa3b, v104
	v_exp_f32_e32 v100, v100
	v_pk_mul_f32 v[98:99], v[102:103], v[98:99] op_sel_hi:[0,1]
	v_pk_mul_f32 v[96:97], v[102:103], v[96:97] op_sel_hi:[0,1]
	v_mul_f32_e32 v103, 0xbfb8aa3b, v106
	v_add_f32_e32 v100, 1.0, v100
	v_rcp_f32_e32 v100, v100
	v_exp_f32_e32 v103, v103
	v_lshlrev_b32_e32 v105, 16, v144
	v_and_b32_e32 v107, 0xffff0000, v144
	v_pk_mul_f32 v[104:105], v[100:101], v[104:105]
	s_andn2_b64 vcc, exec, s[16:17]
	v_add_f32_e32 v96, v105, v96
	v_mul_f32_e32 v108, v104, v96
	v_add_f32_e32 v96, 1.0, v103
	v_rcp_f32_e32 v100, v96
	v_lshlrev_b32_e32 v96, 16, v147
	v_mul_f32_e32 v103, 0xbfb8aa3b, v96
	v_exp_f32_e32 v103, v103
	v_pk_mul_f32 v[104:105], v[100:101], v[106:107]
	v_and_b32_e32 v106, 0xffff0000, v147
	v_add_f32_e32 v97, v105, v97
	v_add_f32_e32 v100, 1.0, v103
	v_mul_f32_e32 v103, 0xbfb8aa3b, v106
	v_rcp_f32_e32 v100, v100
	v_exp_f32_e32 v103, v103
	v_mul_f32_e32 v104, v104, v97
	v_lshlrev_b32_e32 v97, 16, v145
	v_pk_mul_f32 v[96:97], v[100:101], v[96:97]
	v_add_f32_e32 v100, 1.0, v103
	v_rcp_f32_e32 v100, v100
	v_add_f32_e32 v97, v97, v98
	v_and_b32_e32 v107, 0xffff0000, v145
	v_mul_f32_e32 v98, v96, v97
	v_pk_mul_f32 v[96:97], v[100:101], v[106:107]
	v_pk_mul_f32 v[92:93], v[102:103], v[92:93] op_sel_hi:[0,1]
	v_add_f32_e32 v97, v97, v99
	v_mul_f32_e32 v97, v96, v97
	v_cvt_pk_bf16_f32 v96, v108, v104
	v_cvt_pk_bf16_f32 v97, v98, v97
	v_mov_b32_e32 v214, v96
	v_mov_b32_e32 v215, v97
	v_add_u32_e32 v225, v224, v165
	s_nop 0
	v_permlane16_swap_b32_e32 v212, v214
	v_permlane16_swap_b32_e32 v213, v215
	global_store_dwordx4 v225, v[212:215], s[18:19]
	s_waitcnt vmcnt(3)
	v_permlane16_swap_b32_e32 v140, v142
	v_permlane16_swap_b32_e32 v141, v143
	v_permlane16_swap_b32_e32 v136, v138
	v_permlane16_swap_b32_e32 v137, v139
	v_swap_b32 v142, v136
	v_swap_b32 v143, v137
	v_lshlrev_b32_e32 v96, 16, v142
	v_mul_f32_e32 v97, 0xbfb8aa3b, v96
	v_exp_f32_e32 v98, v97
	v_lshlrev_b32_e32 v97, 16, v140
	v_pk_mul_f32 v[94:95], v[102:103], v[94:95] op_sel_hi:[0,1]
	v_mov_b64_e32 v[124:125], v[64:65]
	v_add_f32_e32 v98, 1.0, v98
	v_rcp_f32_e32 v100, v98
	v_and_b32_e32 v98, 0xffff0000, v142
	v_mul_f32_e32 v99, 0xbfb8aa3b, v98
	v_exp_f32_e32 v99, v99
	v_pk_mul_f32 v[96:97], v[100:101], v[96:97]
	v_mov_b64_e32 v[120:121], v[76:77]
	v_add_f32_e32 v92, v97, v92
	v_mul_f32_e32 v103, v96, v92
	v_add_f32_e32 v92, 1.0, v99
	v_rcp_f32_e32 v100, v92
	v_lshlrev_b32_e32 v92, 16, v143
	v_mul_f32_e32 v96, 0xbfb8aa3b, v92
	v_exp_f32_e32 v104, v96
	v_and_b32_e32 v99, 0xffff0000, v140
	v_pk_mul_f32 v[96:97], v[100:101], v[98:99]
	v_and_b32_e32 v98, 0xffff0000, v143
	v_add_f32_e32 v93, v97, v93
	v_add_f32_e32 v97, 1.0, v104
	v_rcp_f32_e32 v100, v97
	v_mul_f32_e32 v97, 0xbfb8aa3b, v98
	v_exp_f32_e32 v97, v97
	v_mul_f32_e32 v96, v96, v93
	v_lshlrev_b32_e32 v93, 16, v141
	v_pk_mul_f32 v[92:93], v[100:101], v[92:93]
	v_add_f32_e32 v97, 1.0, v97
	v_rcp_f32_e32 v100, v97
	v_add_f32_e32 v93, v93, v94
	v_and_b32_e32 v99, 0xffff0000, v141
	v_mul_f32_e32 v94, v92, v93
	v_pk_mul_f32 v[92:93], v[100:101], v[98:99]
	v_pk_mul_f32 v[88:89], v[102:103], v[88:89] op_sel_hi:[0,1]
	v_add_f32_e32 v93, v93, v95
	v_mul_f32_e32 v93, v92, v93
	v_cvt_pk_bf16_f32 v92, v103, v96
	v_cvt_pk_bf16_f32 v93, v94, v93
	v_mov_b32_e32 v216, v92
	v_mov_b32_e32 v217, v93
	s_waitcnt vmcnt(3)
; __device__ __forceinline__ unsigned cvt_pk_bf16(float lo, float hi) { unsigned r; asm volatile("v_cvt_pk_bf16_f32 %0, %1, %2" : "=v"(r) : "v"(lo), "v"(hi)); return r; }
; __device__ __forceinline__ float silu_f(float x) { return x * __builtin_amdgcn_rcpf(1.0f + __builtin_amdgcn_exp2f(-x * LOG2E)); }
;     ...
;         for (int db = 0; db < 8; ++db) { f32x4 v = o[db] * wb;
;             const size_t ocol = (size_t)h * 128 + 16 * db + 4 * fq;
;             if (PASS > 0) { v[0] += wa * bf_lo(pv[db].x); v[1] += wa * bf_hi(pv[db].x); v[2] += wa * bf_lo(pv[db].y); v[3] += wa * bf_hi(pv[db].y); }
;             if (PASS < 2) { u32x2 ov; ov.x = pg8::cvt_pk_bf16(v[0], v[1]); ov.y = pg8::cvt_pk_bf16(v[2], v[3]); *(u32x2*)((char*)OACC + ((unsigned)(h * MT + qrow) * 256u + (unsigned)(32 * db + 8 * fq))) = ov; }
;             else { v[0] *= pg8::silu_f(bf_lo(gv[db].x)); v[1] *= pg8::silu_f(bf_hi(gv[db].x)); v[2] *= pg8::silu_f(bf_lo(gv[db].y)); v[3] *= pg8::silu_f(bf_hi(gv[db].y));
;                 u32x2 ov; ov.x = pg8::cvt_pk_bf16(v[0], v[1]); ov.y = pg8::cvt_pk_bf16(v[2], v[3]); *(u32x2*)((char*)RB + ((unsigned)qrow * (unsigned)(LDB * 2) + (unsigned)(h * 256 + 32 * db + 8 * fq))) = ov; } }
;         asm volatile("s_waitcnt lgkmcnt(0)\n\ts_barrier" ::: "memory");
	v_lshlrev_b32_e32 v92, 16, v138
	v_mul_f32_e32 v93, 0xbfb8aa3b, v92
	v_exp_f32_e32 v94, v93
	v_lshlrev_b32_e32 v93, 16, v136
	v_pk_mul_f32 v[90:91], v[102:103], v[90:91] op_sel_hi:[0,1]
	v_pk_mul_f32 v[84:85], v[102:103], v[84:85] op_sel_hi:[0,1]
	v_add_f32_e32 v94, 1.0, v94
	v_rcp_f32_e32 v100, v94
	v_and_b32_e32 v94, 0xffff0000, v138
	v_mul_f32_e32 v95, 0xbfb8aa3b, v94
	v_exp_f32_e32 v95, v95
	v_pk_mul_f32 v[92:93], v[100:101], v[92:93]
	v_pk_mul_f32 v[86:87], v[102:103], v[86:87] op_sel_hi:[0,1]
	v_add_f32_e32 v88, v93, v88
	v_mul_f32_e32 v96, v92, v88
	v_add_f32_e32 v88, 1.0, v95
	v_rcp_f32_e32 v100, v88
	v_lshlrev_b32_e32 v88, 16, v139
	v_mul_f32_e32 v92, 0xbfb8aa3b, v88
	v_exp_f32_e32 v97, v92
	v_and_b32_e32 v95, 0xffff0000, v136
	v_pk_mul_f32 v[92:93], v[100:101], v[94:95]
	v_and_b32_e32 v94, 0xffff0000, v139
	v_add_f32_e32 v89, v93, v89
	v_add_f32_e32 v93, 1.0, v97
	v_rcp_f32_e32 v100, v93
	v_mul_f32_e32 v93, 0xbfb8aa3b, v94
	v_exp_f32_e32 v93, v93
	v_mul_f32_e32 v92, v92, v89
	v_lshlrev_b32_e32 v89, 16, v137
	v_pk_mul_f32 v[88:89], v[100:101], v[88:89]
	v_add_f32_e32 v93, 1.0, v93
	v_rcp_f32_e32 v100, v93
	v_add_f32_e32 v89, v89, v90
	v_and_b32_e32 v95, 0xffff0000, v137
	v_mul_f32_e32 v90, v88, v89
	v_pk_mul_f32 v[88:89], v[100:101], v[94:95]
	v_pk_mul_f32 v[80:81], v[102:103], v[80:81] op_sel_hi:[0,1]
	v_add_f32_e32 v89, v89, v91
	v_mul_f32_e32 v89, v88, v89
	v_cvt_pk_bf16_f32 v88, v96, v92
	v_cvt_pk_bf16_f32 v89, v90, v89
	v_mov_b32_e32 v218, v88
	v_mov_b32_e32 v219, v89
	v_add_u32_e32 v225, v224, v163
	s_nop 0
	v_permlane16_swap_b32_e32 v216, v218
	v_permlane16_swap_b32_e32 v217, v219
	global_store_dwordx4 v225, v[216:219], s[18:19]
	s_waitcnt vmcnt(3)
	v_permlane16_swap_b32_e32 v132, v134
	v_permlane16_swap_b32_e32 v133, v135
	v_permlane16_swap_b32_e32 v128, v130
	v_permlane16_swap_b32_e32 v129, v131
	v_swap_b32 v134, v128
	v_swap_b32 v135, v129
	v_lshlrev_b32_e32 v88, 16, v134
	v_mul_f32_e32 v89, 0xbfb8aa3b, v88
	v_exp_f32_e32 v90, v89
	v_lshlrev_b32_e32 v89, 16, v132
	v_pk_mul_f32 v[82:83], v[102:103], v[82:83] op_sel_hi:[0,1]
	s_mov_b32 s2, s30
	v_add_f32_e32 v90, 1.0, v90
	v_rcp_f32_e32 v100, v90
	v_and_b32_e32 v90, 0xffff0000, v134
	v_mul_f32_e32 v91, 0xbfb8aa3b, v90
	v_exp_f32_e32 v91, v91
	v_pk_mul_f32 v[88:89], v[100:101], v[88:89]
	s_nop 0
	v_add_f32_e32 v84, v89, v84
	v_mul_f32_e32 v92, v88, v84
	v_add_f32_e32 v84, 1.0, v91
	v_rcp_f32_e32 v100, v84
	v_lshlrev_b32_e32 v84, 16, v135
	v_mul_f32_e32 v88, 0xbfb8aa3b, v84
	v_exp_f32_e32 v93, v88
	v_and_b32_e32 v91, 0xffff0000, v132
	v_pk_mul_f32 v[88:89], v[100:101], v[90:91]
	v_and_b32_e32 v90, 0xffff0000, v135
	v_add_f32_e32 v85, v89, v85
	v_add_f32_e32 v89, 1.0, v93
	v_rcp_f32_e32 v100, v89
	v_mul_f32_e32 v89, 0xbfb8aa3b, v90
	v_exp_f32_e32 v89, v89
	v_mul_f32_e32 v88, v88, v85
	v_lshlrev_b32_e32 v85, 16, v133
	v_pk_mul_f32 v[84:85], v[100:101], v[84:85]
	v_add_f32_e32 v89, 1.0, v89
	v_rcp_f32_e32 v100, v89
	v_add_f32_e32 v85, v85, v86
	v_and_b32_e32 v91, 0xffff0000, v133
	v_mul_f32_e32 v86, v84, v85
	v_pk_mul_f32 v[84:85], v[100:101], v[90:91]
	v_mov_b64_e32 v[134:135], v[74:75]
	v_add_f32_e32 v85, v85, v87
	v_mul_f32_e32 v85, v84, v85
	v_cvt_pk_bf16_f32 v84, v92, v88
	v_cvt_pk_bf16_f32 v85, v86, v85
	v_mov_b32_e32 v220, v84
	v_mov_b32_e32 v221, v85
	s_waitcnt vmcnt(3)
	v_lshlrev_b32_e32 v84, 16, v130
	v_mul_f32_e32 v85, 0xbfb8aa3b, v84
	v_exp_f32_e32 v86, v85
	v_lshlrev_b32_e32 v85, 16, v128
	v_mov_b64_e32 v[132:133], v[72:73]
	v_add_f32_e32 v86, 1.0, v86
	v_rcp_f32_e32 v100, v86
	v_and_b32_e32 v86, 0xffff0000, v130
	v_mul_f32_e32 v87, 0xbfb8aa3b, v86
	v_exp_f32_e32 v87, v87
	v_pk_mul_f32 v[84:85], v[100:101], v[84:85]
	s_nop 0
	v_add_f32_e32 v80, v85, v80
	v_mul_f32_e32 v88, v84, v80
	v_add_f32_e32 v80, 1.0, v87
	v_rcp_f32_e32 v100, v80
	v_lshlrev_b32_e32 v80, 16, v131
	v_mul_f32_e32 v84, 0xbfb8aa3b, v80
	v_exp_f32_e32 v89, v84
	v_and_b32_e32 v87, 0xffff0000, v128
	v_pk_mul_f32 v[84:85], v[100:101], v[86:87]
	v_and_b32_e32 v86, 0xffff0000, v131
	v_add_f32_e32 v81, v85, v81
	v_add_f32_e32 v85, 1.0, v89
	v_rcp_f32_e32 v100, v85
	v_mul_f32_e32 v85, 0xbfb8aa3b, v86
	v_exp_f32_e32 v85, v85
	v_mul_f32_e32 v84, v84, v81
	v_lshlrev_b32_e32 v81, 16, v129
	v_pk_mul_f32 v[80:81], v[100:101], v[80:81]
	v_add_f32_e32 v85, 1.0, v85
	v_rcp_f32_e32 v100, v85
	v_add_f32_e32 v81, v81, v82
	v_and_b32_e32 v87, 0xffff0000, v129
	v_mul_f32_e32 v82, v80, v81
	v_pk_mul_f32 v[80:81], v[100:101], v[86:87]
	v_mov_b64_e32 v[130:131], v[70:71]
	v_add_f32_e32 v81, v81, v83
	v_mul_f32_e32 v81, v80, v81
	v_cvt_pk_bf16_f32 v80, v88, v84
	v_cvt_pk_bf16_f32 v81, v82, v81
	v_mov_b32_e32 v222, v80
	v_mov_b32_e32 v223, v81
	v_add_u32_e32 v225, v224, v161
	s_nop 0
	v_permlane16_swap_b32_e32 v220, v222
	v_permlane16_swap_b32_e32 v221, v223
	global_store_dwordx4 v225, v[220:223], s[18:19]
	s_waitcnt lgkmcnt(0)
	s_barrier
	v_mov_b64_e32 v[128:129], v[68:69]
	s_cbranch_vccz .LBB0_631
